# gate_up GEMM K-loop: LDS-DMA staging rebalanced 4+4 per K-tile (was 2+6) with re-derived counted waits (SP1 vmcnt(8), SP2 vmcnt(6))
# speedup vs baseline: 1.0042x; 1.0011x over previous
; #define PG8_STAGE(bufoff, gbase, voff) do { _Pragma("unroll") for (int _i = 0; _i < 2; ++_i) \
;         __builtin_amdgcn_global_load_lds((const unsigned*)((const char*)(gbase) + (voff)[_i]), (PG8_LAS unsigned*)(lds + (bufoff) + ldsw + _i * 8192), 16, 0, 0); } while (0)
; #define PG8_WAIT_V(n) asm volatile("s_waitcnt vmcnt(" #n ")" ::: "memory")
; #define PG8_BAR __builtin_amdgcn_s_barrier()
; template <class Epi, class Sched, bool ALIGN_EPI = false, bool SP2 = false>
; __device__ __forceinline__ void gemm_phase(PG8_LAS unsigned char* lds, const Gemm g, const Sched& S, const Epi& E) {
;     ...
;     if constexpr (SP2) {
;         PG8_STAGE(PG8_SB(0, 0), cB, voffB); PG8_STAGE(PG8_SB(0, 1), cB + hstep, voffB); PG8_STAGE(PG8_SA(0, 0), cA, voffA); PG8_STAGE(PG8_SA(0, 1), cA + hstep, voffA);
;         if (wr == 1) PG8_BAR;
;         PG8_WAIT_V(2); PG8_BAR;
;         PG8_STAGE(PG8_SB(1, 0), cB + kstep, voffB); PG8_STAGE(PG8_SA(1, 0), cA + kstep, voffA); PG8_STAGE(PG8_SB(1, 1), cB + hstep + kstep, voffB);
;         PG8_WAIT_V(6); PG8_BAR;
.LBB0_1112:
	v_and_b32_e32 v15, 15, v11
	v_and_b32_e32 v16, 48, v11
	v_lshlrev_b32_e32 v11, 2, v11
	s_sext_i32_i16 s17, s2
	v_lshl_or_b32 v143, s3, 6, v15
	v_lshl_or_b32 v15, v15, 6, v16
	s_lshl_b32 s2, s3, 13
	v_and_b32_e32 v11, 32, v11
	v_bitop3_b32 v18, v15, s2, v11 bitop3:0xde
	s_lshl_b32 s2, s7, 5
	s_and_b32 s7, s2, 0x60
	s_add_i32 m0, s28, 0x18000
	v_lshl_add_u64 v[6:7], v[6:7], 0, s[8:9]
	s_lshl_b32 s2, s7, 7
	s_waitcnt vmcnt(2)
	s_barrier
	global_load_lds_dwordx4 v[6:7], off
	v_lshl_add_u64 v[4:5], v[4:5], 0, s[8:9]
	s_add_i32 m0, s28, 0x1a000
	s_add_i32 s33, s28, 0x8000
	s_add_i32 s34, s28, 0xa000
	v_bitop3_b32 v144, v15, s2, v11 bitop3:0xde
	global_load_lds_dwordx4 v[4:5], off
	v_lshl_add_u64 v[0:1], v[0:1], 0, s[8:9]
	s_mov_b32 m0, s33
	s_add_u32 s2, s20, 0x40080
	v_lshl_add_u64 v[0:1], v[2:3], 0, s[8:9]
	s_mov_b32 m0, s34
	s_addc_u32 s3, s21, 0
	s_add_i32 m0, s28, 0x1c000
	v_lshl_add_u64 v[0:1], s[2:3], 0, v[188:189]
	global_load_lds_dwordx4 v[0:1], off
	v_lshl_add_u64 v[0:1], s[2:3], 0, v[132:133]
	s_add_i32 m0, s28, 0x1e000
	s_cmpk_lt_u32 s6, 0x100
	global_load_lds_dwordx4 v[0:1], off
	v_lshlrev_b32_e32 v0, 14, v8
	v_and_b32_e32 v0, 0xffff8000, v0
	v_lshl_add_u32 v0, v9, 11, v0
	v_and_b32_e32 v1, 1, v8
	v_lshl_or_b32 v0, v1, 6, v0
	v_lshl_add_u32 v136, v10, 1, v0
	v_lshlrev_b32_e32 v0, 14, v12
	s_cselect_b64 s[2:3], -1, 0
	s_lshl_b32 s6, s7, 1
	v_readlane_b32 s7, v254, 23
	v_and_b32_e32 v0, 0xffff8000, v0
	s_waitcnt vmcnt(4)
	s_add_u32 s6, s7, s6
	v_readlane_b32 s7, v254, 24
	v_lshl_add_u32 v0, v13, 11, v0
	v_and_b32_e32 v1, 1, v12
	s_addc_u32 s7, s7, 0
	v_mov_b32_e32 v17, v189
	v_lshl_or_b32 v0, v1, 6, v0
	v_lshl_add_u64 v[134:135], s[6:7], 0, v[16:17]
	s_ashr_i32 s35, s24, 31
	v_mov_b32_e32 v137, v189
	v_lshl_add_u32 v138, v14, 1, v0
	v_mov_b32_e32 v139, v189
	s_mov_b32 s36, 0
	v_add_u32_e32 v145, 0, v18
	s_barrier
	s_branch .LBB0_1115

; #define PG8_STAGE(bufoff, gbase, voff) do { _Pragma("unroll") for (int _i = 0; _i < 2; ++_i) \
;         __builtin_amdgcn_global_load_lds((const unsigned*)((const char*)(gbase) + (voff)[_i]), (PG8_LAS unsigned*)(lds + (bufoff) + ldsw + _i * 8192), 16, 0, 0); } while (0)
; #define PG8_LDA(dst, b, h) do { _Pragma("unroll") for (int m = 0; m < 4; ++m) _Pragma("unroll") for (int k = 0; k < 2; ++k) dst[m][k] = *(const PG8_LAS bf16x8*)(lds + PG8_SA(b, h) + aoff + m * 2048 + k * 1024); } while (0)
; #define PG8_LDB(dst, b, h) do { _Pragma("unroll") for (int n = 0; n < 2; ++n) _Pragma("unroll") for (int k = 0; k < 2; ++k) dst[n][k] = *(const PG8_LAS bf16x8*)(lds + PG8_SB(b, h) + boff + n * 2048 + k * 1024); } while (0)
; #define PG8_MMA(ai, bj, At, Bt) do { __builtin_amdgcn_s_setprio(1); _Pragma("unroll") for (int m = 0; m < 4; ++m) _Pragma("unroll") for (int n = 0; n < 2; ++n) _Pragma("unroll") for (int k = 0; k < 2; ++k) \
;         acc[ai][bj][m][n] = __builtin_amdgcn_mfma_f32_16x16x32_bf16(Bt[n][k], At[m][k], acc[ai][bj][m][n], 0, 0, 0); __builtin_amdgcn_s_setprio(0); } while (0)
; #define PG8_WAIT_V(n) asm volatile("s_waitcnt vmcnt(" #n ")" ::: "memory")
; #define PG8_WAIT_L(n) asm volatile("s_waitcnt lgkmcnt(" #n ")" ::: "memory")
; #define PG8_BAR __builtin_amdgcn_s_barrier()
; #define PG8_SCHED __builtin_amdgcn_sched_barrier(0)
; template <class Epi, class Sched, bool ALIGN_EPI = false, bool SP2 = false>
; __device__ __forceinline__ void gemm_phase(PG8_LAS unsigned char* lds, const Gemm g, const Sched& S, const Epi& E) {
;     ...
;             PG8_LDB(B0, 0, 0); PG8_LDB(B1, 0, 1); PG8_SCHED; PG8_LDA(At, 0, 0); PG8_STAGE(PG8_SA(1, 1), a1 + hstep, voffA);
;             PG8_WAIT_V(8); PG8_WAIT_L(0); PG8_BAR; PG8_MMA(0, 0, At, B0); PG8_MMA(0, 1, At, B1); PG8_BAR; PG8_SCHED;
;             PG8_LDA(At, 0, 1); PG8_STAGE(PG8_SB(0, 0), b2, voffB); PG8_STAGE(PG8_SB(0, 1), b2 + hstep, voffB); PG8_STAGE(PG8_SA(0, 0), a2, voffA);
;             PG8_WAIT_V(8); PG8_WAIT_L(0); PG8_BAR; PG8_MMA(1, 0, At, B0); PG8_MMA(1, 1, At, B1); PG8_BAR; PG8_SCHED;
.LBB0_1120:
	s_add_u32 s20, s18, 0xfffc0080
	s_addc_u32 s21, s19, -1
	s_add_i32 s42, 0, 0x10000
	s_cmp_eq_u32 s41, 12
	s_cselect_b32 s23, s11, s21
	s_cselect_b32 s22, s37, s20
	v_add_u32_e32 v140, s42, v144
	s_cselect_b32 s21, s9, s40
	s_cselect_b32 s20, s38, s39
	s_add_i32 s44, 0, 0x14000
	ds_read_b128 v[146:149], v140
	ds_read_b128 v[150:153], v140 offset:1024
	ds_read_b128 v[154:157], v140 offset:2048
	ds_read_b128 v[158:161], v140 offset:3072
	v_add_u32_e32 v140, s44, v144
	ds_read_b128 v[162:165], v140
	ds_read_b128 v[166:169], v140 offset:1024
	ds_read_b128 v[170:173], v140 offset:2048
	ds_read_b128 v[174:177], v140 offset:3072
	s_add_u32 vcc_lo, s18, 0xfffc0000
	s_addc_u32 vcc_hi, s19, -1
	v_lshl_add_u64 v[140:141], vcc, 0, v[136:137]
	s_mov_b32 m0, s33
	s_nop 0
	global_load_lds_dwordx4 v[140:141], off
	v_lshl_add_u64 v[140:141], vcc, 0, v[138:139]
	s_mov_b32 m0, s34
	s_nop 0
	global_load_lds_dwordx4 v[140:141], off
	v_lshl_add_u64 v[140:141], s[18:19], 0, v[136:137]
	s_add_i32 m0, s28, 0xc000
	ds_read_b128 v[178:181], v145
	ds_read_b128 v[182:185], v145 offset:1024
	ds_read_b128 v[194:197], v145 offset:2048
	ds_read_b128 v[198:201], v145 offset:3072
	ds_read_b128 v[202:205], v145 offset:4096
	ds_read_b128 v[210:213], v145 offset:5120
	ds_read_b128 v[214:217], v145 offset:6144
	ds_read_b128 v[218:221], v145 offset:7168
	global_load_lds_dwordx4 v[140:141], off
	v_lshl_add_u64 v[140:141], s[18:19], 0, v[138:139]
	s_add_i32 m0, s28, 0xe000
	s_nop 0
	global_load_lds_dwordx4 v[140:141], off
	s_waitcnt vmcnt(8)
	s_waitcnt lgkmcnt(0)
	s_barrier
	s_setprio 1
	s_waitcnt lgkmcnt(0)
	v_mfma_f32_16x16x32_bf16 v[124:127], v[146:149], v[178:181], v[124:127]
	v_mfma_f32_16x16x32_bf16 v[116:119], v[154:157], v[178:181], v[116:119]
	v_mfma_f32_16x16x32_bf16 v[108:111], v[146:149], v[194:197], v[108:111]
	v_mfma_f32_16x16x32_bf16 v[100:103], v[154:157], v[194:197], v[100:103]
	v_mfma_f32_16x16x32_bf16 v[92:95], v[146:149], v[202:205], v[92:95]
	v_mfma_f32_16x16x32_bf16 v[84:87], v[154:157], v[202:205], v[84:87]
	v_mfma_f32_16x16x32_bf16 v[76:79], v[146:149], v[214:217], v[76:79]
	v_mfma_f32_16x16x32_bf16 v[68:71], v[154:157], v[214:217], v[68:71]
	v_mfma_f32_16x16x32_bf16 v[124:127], v[150:153], v[182:185], v[124:127]
	v_mfma_f32_16x16x32_bf16 v[116:119], v[158:161], v[182:185], v[116:119]
	v_mfma_f32_16x16x32_bf16 v[108:111], v[150:153], v[198:201], v[108:111]
	v_mfma_f32_16x16x32_bf16 v[100:103], v[158:161], v[198:201], v[100:103]
	v_mfma_f32_16x16x32_bf16 v[92:95], v[150:153], v[210:213], v[92:95]
	v_mfma_f32_16x16x32_bf16 v[84:87], v[158:161], v[210:213], v[84:87]
	v_mfma_f32_16x16x32_bf16 v[76:79], v[150:153], v[218:221], v[76:79]
	v_mfma_f32_16x16x32_bf16 v[68:71], v[158:161], v[218:221], v[68:71]
	s_setprio 0
	s_setprio 1
	v_mfma_f32_16x16x32_bf16 v[120:123], v[162:165], v[178:181], v[120:123]
	v_mfma_f32_16x16x32_bf16 v[112:115], v[170:173], v[178:181], v[112:115]
	v_mfma_f32_16x16x32_bf16 v[104:107], v[162:165], v[194:197], v[104:107]
	v_mfma_f32_16x16x32_bf16 v[96:99], v[170:173], v[194:197], v[96:99]
	v_mfma_f32_16x16x32_bf16 v[88:91], v[162:165], v[202:205], v[88:91]
	v_mfma_f32_16x16x32_bf16 v[80:83], v[170:173], v[202:205], v[80:83]
	v_mfma_f32_16x16x32_bf16 v[72:75], v[162:165], v[214:217], v[72:75]
	v_mfma_f32_16x16x32_bf16 v[64:67], v[170:173], v[214:217], v[64:67]
	v_mfma_f32_16x16x32_bf16 v[120:123], v[166:169], v[182:185], v[120:123]
	v_mfma_f32_16x16x32_bf16 v[112:115], v[174:177], v[182:185], v[112:115]
	v_mfma_f32_16x16x32_bf16 v[104:107], v[166:169], v[198:201], v[104:107]
	v_mfma_f32_16x16x32_bf16 v[96:99], v[174:177], v[198:201], v[96:99]
	v_mfma_f32_16x16x32_bf16 v[88:91], v[166:169], v[210:213], v[88:91]
	v_mfma_f32_16x16x32_bf16 v[80:83], v[174:177], v[210:213], v[80:83]
	v_mfma_f32_16x16x32_bf16 v[72:75], v[166:169], v[218:221], v[72:75]
	v_mfma_f32_16x16x32_bf16 v[64:67], v[174:177], v[218:221], v[64:67]
	s_setprio 0
	s_barrier
	s_add_i32 s42, s42, s27
	v_lshl_add_u64 v[140:141], s[20:21], 0, v[188:189]
	s_mov_b32 m0, s42
	ds_read_b128 v[178:181], v145 offset:16384
	ds_read_b128 v[182:185], v145 offset:17408
	ds_read_b128 v[194:197], v145 offset:18432
	ds_read_b128 v[198:201], v145 offset:19456
	ds_read_b128 v[202:205], v145 offset:20480
	ds_read_b128 v[210:213], v145 offset:21504
	ds_read_b128 v[214:217], v145 offset:22528
	ds_read_b128 v[218:221], v145 offset:23552
	global_load_lds_dwordx4 v[140:141], off
	s_add_i32 m0, s42, 0x2000
	s_add_u32 s42, s20, 0x40000
	v_lshl_add_u64 v[186:187], s[20:21], 0, v[132:133]
	s_addc_u32 s43, s21, 0
	s_add_i32 s44, s44, s27
	global_load_lds_dwordx4 v[186:187], off
	v_lshl_add_u64 v[190:191], s[42:43], 0, v[188:189]
	s_mov_b32 m0, s44
	v_lshl_add_u64 v[222:223], s[22:23], 0, v[130:131]
	global_load_lds_dwordx4 v[190:191], off
	v_lshl_add_u64 v[190:191], s[42:43], 0, v[132:133]
	s_add_i32 m0, s44, 0x2000
	s_nop 0
	global_load_lds_dwordx4 v[190:191], off
	s_waitcnt vmcnt(6)
	s_waitcnt lgkmcnt(0)
	s_barrier
; #define PG8_STAGE(bufoff, gbase, voff) do { _Pragma("unroll") for (int _i = 0; _i < 2; ++_i) \
;         __builtin_amdgcn_global_load_lds((const unsigned*)((const char*)(gbase) + (voff)[_i]), (PG8_LAS unsigned*)(lds + (bufoff) + ldsw + _i * 8192), 16, 0, 0); } while (0)
; #define PG8_LDA(dst, b, h) do { _Pragma("unroll") for (int m = 0; m < 4; ++m) _Pragma("unroll") for (int k = 0; k < 2; ++k) dst[m][k] = *(const PG8_LAS bf16x8*)(lds + PG8_SA(b, h) + aoff + m * 2048 + k * 1024); } while (0)
; #define PG8_LDB(dst, b, h) do { _Pragma("unroll") for (int n = 0; n < 2; ++n) _Pragma("unroll") for (int k = 0; k < 2; ++k) dst[n][k] = *(const PG8_LAS bf16x8*)(lds + PG8_SB(b, h) + boff + n * 2048 + k * 1024); } while (0)
; #define PG8_MMA(ai, bj, At, Bt) do { __builtin_amdgcn_s_setprio(1); _Pragma("unroll") for (int m = 0; m < 4; ++m) _Pragma("unroll") for (int n = 0; n < 2; ++n) _Pragma("unroll") for (int k = 0; k < 2; ++k) \
;         acc[ai][bj][m][n] = __builtin_amdgcn_mfma_f32_16x16x32_bf16(Bt[n][k], At[m][k], acc[ai][bj][m][n], 0, 0, 0); __builtin_amdgcn_s_setprio(0); } while (0)
; #define PG8_WAIT_V(n) asm volatile("s_waitcnt vmcnt(" #n ")" ::: "memory")
; #define PG8_WAIT_L(n) asm volatile("s_waitcnt lgkmcnt(" #n ")" ::: "memory")
; #define PG8_BAR __builtin_amdgcn_s_barrier()
; #define PG8_SCHED __builtin_amdgcn_sched_barrier(0)
; template <class Epi, class Sched, bool ALIGN_EPI = false, bool SP2 = false>
; __device__ __forceinline__ void gemm_phase(PG8_LAS unsigned char* lds, const Gemm g, const Sched& S, const Epi& E) {
;     ...
;             PG8_WAIT_V(8); PG8_WAIT_L(0); PG8_BAR; PG8_MMA(1, 0, At, B0); PG8_MMA(1, 1, At, B1); PG8_BAR; PG8_SCHED;
;             PG8_LDB(B0, 1, 0); PG8_LDB(B1, 1, 1); PG8_SCHED; PG8_LDA(At, 1, 0); PG8_STAGE(PG8_SA(0, 1), a2 + hstep, voffA);
;             PG8_WAIT_V(8); PG8_WAIT_L(0); PG8_BAR; PG8_MMA(0, 0, At, B0); PG8_MMA(0, 1, At, B1); PG8_BAR; PG8_SCHED;
	s_setprio 1
	s_waitcnt lgkmcnt(0)
	v_mfma_f32_16x16x32_bf16 v[60:63], v[146:149], v[178:181], v[60:63]
	v_mfma_f32_16x16x32_bf16 v[52:55], v[154:157], v[178:181], v[52:55]
	v_mfma_f32_16x16x32_bf16 v[44:47], v[146:149], v[194:197], v[44:47]
	v_mfma_f32_16x16x32_bf16 v[36:39], v[154:157], v[194:197], v[36:39]
	v_mfma_f32_16x16x32_bf16 v[28:31], v[146:149], v[202:205], v[28:31]
	v_mfma_f32_16x16x32_bf16 v[20:23], v[154:157], v[202:205], v[20:23]
	v_mfma_f32_16x16x32_bf16 v[12:15], v[146:149], v[214:217], v[12:15]
	v_mfma_f32_16x16x32_bf16 v[4:7], v[154:157], v[214:217], v[4:7]
	v_mfma_f32_16x16x32_bf16 v[60:63], v[150:153], v[182:185], v[60:63]
	v_mfma_f32_16x16x32_bf16 v[52:55], v[158:161], v[182:185], v[52:55]
	v_mfma_f32_16x16x32_bf16 v[44:47], v[150:153], v[198:201], v[44:47]
	v_mfma_f32_16x16x32_bf16 v[36:39], v[158:161], v[198:201], v[36:39]
	v_mfma_f32_16x16x32_bf16 v[28:31], v[150:153], v[210:213], v[28:31]
	v_mfma_f32_16x16x32_bf16 v[20:23], v[158:161], v[210:213], v[20:23]
	v_mfma_f32_16x16x32_bf16 v[12:15], v[150:153], v[218:221], v[12:15]
	v_mfma_f32_16x16x32_bf16 v[4:7], v[158:161], v[218:221], v[4:7]
	s_setprio 0
	s_setprio 1
	v_mfma_f32_16x16x32_bf16 v[56:59], v[162:165], v[178:181], v[56:59]
	v_mfma_f32_16x16x32_bf16 v[48:51], v[170:173], v[178:181], v[48:51]
	v_mfma_f32_16x16x32_bf16 v[40:43], v[162:165], v[194:197], v[40:43]
	v_mfma_f32_16x16x32_bf16 v[32:35], v[170:173], v[194:197], v[32:35]
	v_mfma_f32_16x16x32_bf16 v[24:27], v[162:165], v[202:205], v[24:27]
	v_mfma_f32_16x16x32_bf16 v[16:19], v[170:173], v[202:205], v[16:19]
	v_mfma_f32_16x16x32_bf16 v[8:11], v[162:165], v[214:217], v[8:11]
	v_mfma_f32_16x16x32_bf16 v[0:3], v[170:173], v[214:217], v[0:3]
	v_mfma_f32_16x16x32_bf16 v[56:59], v[166:169], v[182:185], v[56:59]
	v_mfma_f32_16x16x32_bf16 v[48:51], v[174:177], v[182:185], v[48:51]
	v_mfma_f32_16x16x32_bf16 v[40:43], v[166:169], v[198:201], v[40:43]
	v_mfma_f32_16x16x32_bf16 v[32:35], v[174:177], v[198:201], v[32:35]
	v_mfma_f32_16x16x32_bf16 v[24:27], v[166:169], v[210:213], v[24:27]
	v_mfma_f32_16x16x32_bf16 v[16:19], v[174:177], v[210:213], v[16:19]
	v_mfma_f32_16x16x32_bf16 v[8:11], v[166:169], v[218:221], v[8:11]
	v_mfma_f32_16x16x32_bf16 v[0:3], v[174:177], v[218:221], v[0:3]
	s_setprio 0
	s_barrier
	s_add_i32 s42, 0, 0x18000
	s_add_i32 s43, 0, 0x1c000
	v_add_u32_e32 v158, s42, v144
	v_add_u32_e32 v174, s43, v144
	ds_read_b128 v[146:149], v158
	ds_read_b128 v[150:153], v158 offset:1024
	ds_read_b128 v[154:157], v158 offset:2048
	ds_read_b128 v[158:161], v158 offset:3072
	ds_read_b128 v[162:165], v174
	ds_read_b128 v[166:169], v174 offset:1024
	ds_read_b128 v[170:173], v174 offset:2048
	ds_read_b128 v[174:177], v174 offset:3072
	v_lshl_add_u64 v[224:225], s[22:23], 0, v[128:129]
	s_mov_b32 m0, s28
	s_nop 0
	global_load_lds_dwordx4 v[224:225], off
	v_lshl_add_u64 v[224:225], s[22:23], 0, v[130:131]
	s_mov_b32 m0, s29
	s_nop 0
	global_load_lds_dwordx4 v[224:225], off
	s_add_u32 s22, s22, 0x40000
	s_addc_u32 s23, s23, 0
	s_mov_b32 m0, s30
	v_lshl_add_u64 v[224:225], s[22:23], 0, v[128:129]
	ds_read_b128 v[178:181], v145 offset:32768
	ds_read_b128 v[182:185], v145 offset:33792
	ds_read_b128 v[194:197], v145 offset:34816
	ds_read_b128 v[198:201], v145 offset:35840
	ds_read_b128 v[202:205], v145 offset:36864
	ds_read_b128 v[210:213], v145 offset:37888
	ds_read_b128 v[214:217], v145 offset:38912
	ds_read_b128 v[218:221], v145 offset:39936
	global_load_lds_dwordx4 v[224:225], off
	v_lshl_add_u64 v[224:225], s[22:23], 0, v[130:131]
	s_mov_b32 m0, s31
	s_nop 0
	global_load_lds_dwordx4 v[224:225], off
	s_waitcnt vmcnt(8)
	s_waitcnt lgkmcnt(0)
	s_barrier
; #define PG8_STAGE(bufoff, gbase, voff) do { _Pragma("unroll") for (int _i = 0; _i < 2; ++_i) \
;         __builtin_amdgcn_global_load_lds((const unsigned*)((const char*)(gbase) + (voff)[_i]), (PG8_LAS unsigned*)(lds + (bufoff) + ldsw + _i * 8192), 16, 0, 0); } while (0)
; #define PG8_LDA(dst, b, h) do { _Pragma("unroll") for (int m = 0; m < 4; ++m) _Pragma("unroll") for (int k = 0; k < 2; ++k) dst[m][k] = *(const PG8_LAS bf16x8*)(lds + PG8_SA(b, h) + aoff + m * 2048 + k * 1024); } while (0)
; #define PG8_MMA(ai, bj, At, Bt) do { __builtin_amdgcn_s_setprio(1); _Pragma("unroll") for (int m = 0; m < 4; ++m) _Pragma("unroll") for (int n = 0; n < 2; ++n) _Pragma("unroll") for (int k = 0; k < 2; ++k) \
;         acc[ai][bj][m][n] = __builtin_amdgcn_mfma_f32_16x16x32_bf16(Bt[n][k], At[m][k], acc[ai][bj][m][n], 0, 0, 0); __builtin_amdgcn_s_setprio(0); } while (0)
; #define PG8_WAIT_V(n) asm volatile("s_waitcnt vmcnt(" #n ")" ::: "memory")
; #define PG8_WAIT_L(n) asm volatile("s_waitcnt lgkmcnt(" #n ")" ::: "memory")
; #define PG8_BAR __builtin_amdgcn_s_barrier()
; #define PG8_SCHED __builtin_amdgcn_sched_barrier(0)
; template <class Epi, class Sched, bool ALIGN_EPI = false, bool SP2 = false>
; __device__ __forceinline__ void gemm_phase(PG8_LAS unsigned char* lds, const Gemm g, const Sched& S, const Epi& E) {
;     ...
;         for (int t = 0; t < nt; t += 2) {
;     ...
;             PG8_WAIT_V(8); PG8_WAIT_L(0); PG8_BAR; PG8_MMA(0, 0, At, B0); PG8_MMA(0, 1, At, B1); PG8_BAR; PG8_SCHED;
;             PG8_LDA(At, 1, 1); PG8_STAGE(PG8_SB(1, 0), b3, voffB); PG8_STAGE(PG8_SB(1, 1), b3 + hstep, voffB); PG8_STAGE(PG8_SA(1, 0), a3, voffA);
;             PG8_WAIT_V(8); PG8_WAIT_L(0); PG8_BAR; PG8_MMA(1, 0, At, B0); PG8_MMA(1, 1, At, B1); PG8_BAR; PG8_SCHED;
	s_setprio 1
	s_waitcnt lgkmcnt(0)
	v_mfma_f32_16x16x32_bf16 v[124:127], v[146:149], v[178:181], v[124:127]
	v_mfma_f32_16x16x32_bf16 v[116:119], v[154:157], v[178:181], v[116:119]
	v_mfma_f32_16x16x32_bf16 v[108:111], v[146:149], v[194:197], v[108:111]
	v_mfma_f32_16x16x32_bf16 v[100:103], v[154:157], v[194:197], v[100:103]
	v_mfma_f32_16x16x32_bf16 v[92:95], v[146:149], v[202:205], v[92:95]
	v_mfma_f32_16x16x32_bf16 v[84:87], v[154:157], v[202:205], v[84:87]
	v_mfma_f32_16x16x32_bf16 v[76:79], v[146:149], v[214:217], v[76:79]
	v_mfma_f32_16x16x32_bf16 v[68:71], v[154:157], v[214:217], v[68:71]
	v_mfma_f32_16x16x32_bf16 v[124:127], v[150:153], v[182:185], v[124:127]
	v_mfma_f32_16x16x32_bf16 v[116:119], v[158:161], v[182:185], v[116:119]
	v_mfma_f32_16x16x32_bf16 v[108:111], v[150:153], v[198:201], v[108:111]
	v_mfma_f32_16x16x32_bf16 v[100:103], v[158:161], v[198:201], v[100:103]
	v_mfma_f32_16x16x32_bf16 v[92:95], v[150:153], v[210:213], v[92:95]
	v_mfma_f32_16x16x32_bf16 v[84:87], v[158:161], v[210:213], v[84:87]
	v_mfma_f32_16x16x32_bf16 v[76:79], v[150:153], v[218:221], v[76:79]
	v_mfma_f32_16x16x32_bf16 v[68:71], v[158:161], v[218:221], v[68:71]
	s_setprio 0
	s_setprio 1
	v_mfma_f32_16x16x32_bf16 v[120:123], v[162:165], v[178:181], v[120:123]
	v_mfma_f32_16x16x32_bf16 v[112:115], v[170:173], v[178:181], v[112:115]
	v_mfma_f32_16x16x32_bf16 v[104:107], v[162:165], v[194:197], v[104:107]
	v_mfma_f32_16x16x32_bf16 v[96:99], v[170:173], v[194:197], v[96:99]
	v_mfma_f32_16x16x32_bf16 v[88:91], v[162:165], v[202:205], v[88:91]
	v_mfma_f32_16x16x32_bf16 v[80:83], v[170:173], v[202:205], v[80:83]
	v_mfma_f32_16x16x32_bf16 v[72:75], v[162:165], v[214:217], v[72:75]
	v_mfma_f32_16x16x32_bf16 v[64:67], v[170:173], v[214:217], v[64:67]
	v_mfma_f32_16x16x32_bf16 v[120:123], v[166:169], v[182:185], v[120:123]
	v_mfma_f32_16x16x32_bf16 v[112:115], v[174:177], v[182:185], v[112:115]
	v_mfma_f32_16x16x32_bf16 v[104:107], v[166:169], v[198:201], v[104:107]
	v_mfma_f32_16x16x32_bf16 v[96:99], v[174:177], v[198:201], v[96:99]
	v_mfma_f32_16x16x32_bf16 v[88:91], v[166:169], v[210:213], v[88:91]
	v_mfma_f32_16x16x32_bf16 v[80:83], v[174:177], v[210:213], v[80:83]
	v_mfma_f32_16x16x32_bf16 v[72:75], v[166:169], v[218:221], v[72:75]
	v_mfma_f32_16x16x32_bf16 v[64:67], v[174:177], v[218:221], v[64:67]
	s_setprio 0
	s_barrier
	s_add_i32 s22, s42, s27
	v_lshl_add_u64 v[140:141], v[140:141], 0, s[48:49]
	s_mov_b32 m0, s22
	ds_read_b128 v[178:181], v145 offset:49152
	ds_read_b128 v[182:185], v145 offset:50176
	ds_read_b128 v[194:197], v145 offset:51200
	ds_read_b128 v[198:201], v145 offset:52224
	ds_read_b128 v[202:205], v145 offset:53248
	ds_read_b128 v[210:213], v145 offset:54272
	ds_read_b128 v[214:217], v145 offset:55296
	ds_read_b128 v[218:221], v145 offset:56320
	global_load_lds_dwordx4 v[140:141], off
	s_add_i32 m0, s22, 0x2000
	s_add_u32 s20, s20, 0x40080
	v_lshl_add_u64 v[140:141], v[186:187], 0, s[48:49]
	s_addc_u32 s21, s21, 0
	s_add_i32 s22, s43, s27
	global_load_lds_dwordx4 v[140:141], off
	v_lshl_add_u64 v[140:141], s[20:21], 0, v[188:189]
	s_mov_b32 m0, s22
	s_nop 0
	global_load_lds_dwordx4 v[140:141], off
	v_lshl_add_u64 v[140:141], s[20:21], 0, v[132:133]
	s_add_i32 m0, s22, 0x2000
	s_nop 0
	global_load_lds_dwordx4 v[140:141], off
	s_waitcnt vmcnt(6)
	s_waitcnt lgkmcnt(0)
	s_barrier
	s_setprio 1
	s_waitcnt lgkmcnt(0)
	v_mfma_f32_16x16x32_bf16 v[60:63], v[146:149], v[178:181], v[60:63]
	v_mfma_f32_16x16x32_bf16 v[52:55], v[154:157], v[178:181], v[52:55]
	v_mfma_f32_16x16x32_bf16 v[44:47], v[146:149], v[194:197], v[44:47]
	v_mfma_f32_16x16x32_bf16 v[36:39], v[154:157], v[194:197], v[36:39]
	v_mfma_f32_16x16x32_bf16 v[28:31], v[146:149], v[202:205], v[28:31]
	v_mfma_f32_16x16x32_bf16 v[20:23], v[154:157], v[202:205], v[20:23]
	v_mfma_f32_16x16x32_bf16 v[12:15], v[146:149], v[214:217], v[12:15]
	v_mfma_f32_16x16x32_bf16 v[4:7], v[154:157], v[214:217], v[4:7]
	v_mfma_f32_16x16x32_bf16 v[60:63], v[150:153], v[182:185], v[60:63]
	v_mfma_f32_16x16x32_bf16 v[52:55], v[158:161], v[182:185], v[52:55]
	v_mfma_f32_16x16x32_bf16 v[44:47], v[150:153], v[198:201], v[44:47]
	v_mfma_f32_16x16x32_bf16 v[36:39], v[158:161], v[198:201], v[36:39]
	v_mfma_f32_16x16x32_bf16 v[28:31], v[150:153], v[210:213], v[28:31]
	v_mfma_f32_16x16x32_bf16 v[20:23], v[158:161], v[210:213], v[20:23]
	v_mfma_f32_16x16x32_bf16 v[12:15], v[150:153], v[218:221], v[12:15]
	v_mfma_f32_16x16x32_bf16 v[4:7], v[158:161], v[218:221], v[4:7]
	s_setprio 0
	s_setprio 1
	v_mfma_f32_16x16x32_bf16 v[56:59], v[162:165], v[178:181], v[56:59]
	v_mfma_f32_16x16x32_bf16 v[48:51], v[170:173], v[178:181], v[48:51]
	v_mfma_f32_16x16x32_bf16 v[40:43], v[162:165], v[194:197], v[40:43]
	v_mfma_f32_16x16x32_bf16 v[32:35], v[170:173], v[194:197], v[32:35]
	v_mfma_f32_16x16x32_bf16 v[24:27], v[162:165], v[202:205], v[24:27]
	v_mfma_f32_16x16x32_bf16 v[16:19], v[170:173], v[202:205], v[16:19]
	v_mfma_f32_16x16x32_bf16 v[8:11], v[162:165], v[214:217], v[8:11]
	v_mfma_f32_16x16x32_bf16 v[0:3], v[170:173], v[214:217], v[0:3]
	v_mfma_f32_16x16x32_bf16 v[56:59], v[166:169], v[182:185], v[56:59]
	v_mfma_f32_16x16x32_bf16 v[48:51], v[174:177], v[182:185], v[48:51]
	v_mfma_f32_16x16x32_bf16 v[40:43], v[166:169], v[198:201], v[40:43]
	v_mfma_f32_16x16x32_bf16 v[32:35], v[174:177], v[198:201], v[32:35]
	v_mfma_f32_16x16x32_bf16 v[24:27], v[166:169], v[210:213], v[24:27]
	v_mfma_f32_16x16x32_bf16 v[16:19], v[174:177], v[210:213], v[16:19]
	v_mfma_f32_16x16x32_bf16 v[8:11], v[166:169], v[218:221], v[8:11]
	v_mfma_f32_16x16x32_bf16 v[0:3], v[174:177], v[218:221], v[0:3]
	s_setprio 0
	s_barrier
	s_add_i32 s41, s41, 2
	s_add_u32 s18, s18, 0x100
	s_addc_u32 s19, s19, 0
	s_add_u32 s39, s39, 0x100
	s_addc_u32 s40, s40, 0
	s_cmp_gt_u32 s41, 13
	s_cbranch_scc0 .LBB0_1120
	s_and_b64 vcc, exec, s[2:3]
	s_cbranch_vccz .LBB0_1123
	s_barrier
